# residual-add epilogue: exact counted waits (stores of the current half may stay in flight while waiting for the next half's residual)
# baseline (speedup 1.0000x reference)
.LBB0_281:
	s_nop 1
	v_cndmask_b32_e64 v144, 0, 1, s[48:49]
	v_cmp_ne_u32_e64 s[46:47], 1, v144
	s_andn2_b64 vcc, exec, s[48:49]
	s_cbranch_vccnz .LBB0_474
	s_and_b64 vcc, exec, s[44:45]
	s_cbranch_vccnz .Le3s_0
	s_waitcnt vmcnt(2)
.Le3b_0:
	v_mov_b32_e32 v148, v236
	v_mov_b32_e32 v149, v237
	v_mov_b32_e32 v150, v238
	v_mov_b32_e32 v151, v239
	v_mov_b32_e32 v144, v240
	v_mov_b32_e32 v145, v241
	v_mov_b32_e32 v146, v242
	v_mov_b32_e32 v147, v243
	v_add_u32_e32 v246, 0x10000, v246
	global_load_dwordx4 v[236:239], v246, s[70:71]
	global_load_dwordx4 v[240:243], v246, s[70:71] offset:16
	s_cbranch_execnz .LBB0_284
.LBB0_283:
	s_and_b64 vcc, exec, s[44:45]
	s_cbranch_vccnz .Le3s_1
	s_waitcnt vmcnt(2)
.Le3b_1:
	v_lshlrev_b32_e32 v148, 16, v236
	v_and_b32_e32 v149, 0xffff0000, v236
	v_lshlrev_b32_e32 v150, 16, v237
	v_and_b32_e32 v151, 0xffff0000, v237
	v_lshlrev_b32_e32 v144, 16, v238
	v_and_b32_e32 v145, 0xffff0000, v238
	v_lshlrev_b32_e32 v146, 16, v239
	v_and_b32_e32 v147, 0xffff0000, v239
	v_add_u32_e32 v246, 0x8000, v246
	global_load_dwordx4 v[236:239], v246, s[68:69]

.LBB0_290:
	v_or_b32_e32 v144, 16, v194
	v_ashrrev_i32_e32 v145, 31, v144
	v_lshlrev_b64 v[144:145], 10, v[144:145]
	v_lshl_add_u64 v[196:197], v[144:145], 0, v[184:185]
	s_and_b64 vcc, exec, s[46:47]
	v_lshl_add_u64 v[210:211], v[196:197], 2, s[70:71]
	s_cbranch_vccnz .LBB0_475
	s_and_b64 vcc, exec, s[44:45]
	s_cbranch_vccnz .Le3s_2
	s_waitcnt vmcnt(3)
.Le3b_2:
	v_mov_b32_e32 v148, v236
	v_mov_b32_e32 v149, v237
	v_mov_b32_e32 v150, v238
	v_mov_b32_e32 v151, v239
	v_mov_b32_e32 v144, v240
	v_mov_b32_e32 v145, v241
	v_mov_b32_e32 v146, v242
	v_mov_b32_e32 v147, v243
	global_load_dwordx4 v[236:239], v246, s[70:71] offset:512
	global_load_dwordx4 v[240:243], v246, s[70:71] offset:528
	v_lshl_add_u64 v[208:209], v[196:197], 1, s[68:69]
	s_cbranch_execnz .LBB0_293
.LBB0_292:
	s_and_b64 vcc, exec, s[44:45]
	s_cbranch_vccnz .Le3s_3
	s_waitcnt vmcnt(3)
.Le3b_3:
	v_lshlrev_b32_e32 v148, 16, v236
	v_and_b32_e32 v149, 0xffff0000, v236
	v_lshlrev_b32_e32 v150, 16, v237
	v_and_b32_e32 v151, 0xffff0000, v237
	v_lshlrev_b32_e32 v144, 16, v238
	v_and_b32_e32 v145, 0xffff0000, v238
	v_lshlrev_b32_e32 v146, 16, v239
	v_and_b32_e32 v147, 0xffff0000, v239
	global_load_dwordx4 v[236:239], v246, s[68:69] offset:256

.LBB0_295:
	s_and_b64 vcc, exec, s[46:47]
	s_cbranch_vccnz .LBB0_476
	s_and_b64 vcc, exec, s[44:45]
	s_cbranch_vccnz .Le3s_4
	s_waitcnt vmcnt(2)

.LBB0_304:
	v_or_b32_e32 v144, 32, v194
	v_ashrrev_i32_e32 v145, 31, v144
	v_lshlrev_b64 v[144:145], 10, v[144:145]
	v_lshl_add_u64 v[196:197], v[144:145], 0, v[184:185]
	s_and_b64 vcc, exec, s[46:47]
	v_lshl_add_u64 v[210:211], v[196:197], 2, s[70:71]
	s_cbranch_vccnz .LBB0_477
	s_and_b64 vcc, exec, s[44:45]
	s_cbranch_vccnz .Le3s_6
	s_waitcnt vmcnt(3)

.LBB0_318:
	v_or_b32_e32 v144, 48, v194
	v_ashrrev_i32_e32 v145, 31, v144
	v_lshlrev_b64 v[144:145], 10, v[144:145]
	v_lshl_add_u64 v[196:197], v[144:145], 0, v[184:185]
	s_and_b64 vcc, exec, s[46:47]
	v_lshl_add_u64 v[210:211], v[196:197], 2, s[70:71]
	s_cbranch_vccnz .LBB0_479
	s_and_b64 vcc, exec, s[44:45]
	s_cbranch_vccnz .Le3s_10
	s_waitcnt vmcnt(3)

.Le3b_12:
	v_mov_b32_e32 v148, v236
	v_mov_b32_e32 v149, v237
	v_mov_b32_e32 v150, v238
	v_mov_b32_e32 v151, v239
	v_mov_b32_e32 v144, v240
	v_mov_b32_e32 v145, v241
	v_mov_b32_e32 v146, v242
	v_mov_b32_e32 v147, v243
	v_add_u32_e32 v246, 0x50000, v246
	global_load_dwordx4 v[236:239], v246, s[70:71]
	global_load_dwordx4 v[240:243], v246, s[70:71] offset:16
	s_cbranch_execnz .LBB0_326

.Le3b_13:
	v_lshlrev_b32_e32 v148, 16, v236
	v_and_b32_e32 v149, 0xffff0000, v236
	v_lshlrev_b32_e32 v150, 16, v237
	v_and_b32_e32 v151, 0xffff0000, v237
	v_lshlrev_b32_e32 v144, 16, v238
	v_and_b32_e32 v145, 0xffff0000, v238
	v_lshlrev_b32_e32 v146, 16, v239
	v_and_b32_e32 v147, 0xffff0000, v239
	v_add_u32_e32 v246, 0x28000, v246
	global_load_dwordx4 v[236:239], v246, s[68:69]

.LBB0_332:
	v_lshlrev_b64 v[144:145], 10, v[194:195]
	v_lshl_add_u64 v[144:145], v[144:145], 0, v[184:185]
	s_mov_b64 s[80:81], 0x20000
	v_lshl_add_u64 v[196:197], v[144:145], 0, s[80:81]
	s_and_b64 vcc, exec, s[46:47]
	v_lshl_add_u64 v[210:211], v[196:197], 2, s[70:71]
	s_cbranch_vccnz .LBB0_481
	s_and_b64 vcc, exec, s[44:45]
	s_cbranch_vccnz .Le3s_14
	s_waitcnt vmcnt(3)

.LBB0_346:
	v_lshlrev_b64 v[144:145], 10, v[194:195]
	v_lshl_add_u64 v[144:145], v[144:145], 0, v[184:185]
	s_mov_b64 s[80:81], 0x24000
	v_lshl_add_u64 v[196:197], v[144:145], 0, s[80:81]
	s_and_b64 vcc, exec, s[46:47]
	v_lshl_add_u64 v[210:211], v[196:197], 2, s[70:71]
	s_cbranch_vccnz .LBB0_483
	s_and_b64 vcc, exec, s[44:45]
	s_cbranch_vccnz .Le3s_18
	s_waitcnt vmcnt(3)

.LBB0_360:
	v_lshlrev_b64 v[144:145], 10, v[194:195]
	v_lshl_add_u64 v[144:145], v[144:145], 0, v[184:185]
	s_mov_b64 s[80:81], 0x28000
	v_lshl_add_u64 v[196:197], v[144:145], 0, s[80:81]
	s_and_b64 vcc, exec, s[46:47]
	v_lshl_add_u64 v[210:211], v[196:197], 2, s[70:71]
	s_cbranch_vccnz .LBB0_485
	s_and_b64 vcc, exec, s[44:45]
	s_cbranch_vccnz .Le3s_22
	s_waitcnt vmcnt(3)

.LBB0_374:
	v_lshlrev_b64 v[144:145], 10, v[194:195]
	v_lshl_add_u64 v[144:145], v[144:145], 0, v[184:185]
	s_mov_b64 s[80:81], 0x2c000
	v_lshl_add_u64 v[194:195], v[144:145], 0, s[80:81]
	s_and_b64 vcc, exec, s[46:47]
	v_lshl_add_u64 v[196:197], v[194:195], 2, s[70:71]
	s_cbranch_vccnz .LBB0_487
	s_and_b64 vcc, exec, s[44:45]
	s_cbranch_vccnz .Le3s_26
	s_waitcnt vmcnt(3)
.Le3b_26:
	v_mov_b32_e32 v148, v236
	v_mov_b32_e32 v149, v237
	v_mov_b32_e32 v150, v238
	v_mov_b32_e32 v151, v239
	v_mov_b32_e32 v144, v240
	v_mov_b32_e32 v145, v241
	v_mov_b32_e32 v146, v242
	v_mov_b32_e32 v147, v243
	global_load_dwordx4 v[236:239], v246, s[70:71] offset:512
	global_load_dwordx4 v[240:243], v246, s[70:71] offset:528
	s_mov_b32 s81, s23
	v_lshl_add_u64 v[198:199], v[194:195], 1, s[68:69]
	s_cbranch_execnz .LBB0_377

.Le3b_28:
	v_mov_b32_e32 v140, v236
	v_mov_b32_e32 v141, v237
	v_mov_b32_e32 v142, v238
	v_mov_b32_e32 v143, v239
	v_mov_b32_e32 v136, v240
	v_mov_b32_e32 v137, v241
	v_mov_b32_e32 v138, v242
	v_mov_b32_e32 v139, v243
	s_cbranch_execnz .LBB0_382

.Le3b_29:
	v_lshlrev_b32_e32 v140, 16, v236
	v_and_b32_e32 v141, 0xffff0000, v236
	v_lshlrev_b32_e32 v142, 16, v237
	v_and_b32_e32 v143, 0xffff0000, v237
	v_lshlrev_b32_e32 v136, 16, v238
	v_and_b32_e32 v137, 0xffff0000, v238
	v_lshlrev_b32_e32 v138, 16, v239
	v_and_b32_e32 v139, 0xffff0000, v239

.Le3s_29:
	s_waitcnt vmcnt(1)
	s_branch .Le3b_29
